# mixer-phase item-loop heads: hgrn stage 1 waits only for the staged loads (vmcnt 14, not for the previous item's 14 output stores) after the first item; attention item head no longer drains the previo
# speedup vs baseline: 1.0170x; 1.0127x over previous
.LBB0_265:
	s_ashr_i32 s0, s5, 7
	s_bfe_u32 s8, s5, 0x50002
	s_ashr_i32 s1, s0, 31
	s_lshl_b64 s[6:7], s[0:1], 12
	s_lshl_b32 s0, s8, 7
	s_and_b32 s12, s5, 3
	s_or_b32 s6, s6, s0
	s_cmp_eq_u32 s8, 0
	v_mov_b32_e32 v4, v216
	s_cselect_b64 s[44:45], -1, 0
	s_cmp_lg_u32 s8, 0
	s_cselect_b64 s[0:1], -1, 0
	v_ashrrev_i32_e32 v138, 2, v4
	v_and_b32_e32 v5, 3, v4
	s_mov_b64 s[8:9], -1
	s_and_b64 vcc, exec, s[0:1]
	v_ashrrev_i32_e32 v139, 31, v138
	v_lshlrev_b32_e32 v168, 3, v5
	s_cbranch_vccz .LBB0_267
	s_add_u32 s10, s6, 0xffffff80
	v_readlane_b32 s8, v246, 36
	s_addc_u32 s11, s7, -1
	v_readlane_b32 s9, v246, 37
	s_waitcnt lgkmcnt(0)
	v_lshl_add_u64 v[0:1], s[10:11], 0, v[138:139]
	s_movk_i32 s4, 0xc00
	v_mov_b64_e32 v[2:3], s[8:9]
	v_mad_u64_u32 v[2:3], s[8:9], v0, s4, v[2:3]
	v_mov_b32_e32 v6, v3
	v_mad_u64_u32 v[6:7], s[8:9], v1, s4, v[6:7]
	v_mov_b32_e32 v3, v6
	s_lshl_b32 s8, s12, 7
	s_mov_b32 s9, s25
	v_lshl_add_u64 v[2:3], v[2:3], 0, s[8:9]
	v_lshlrev_b32_e32 v6, 4, v5
	v_mov_b32_e32 v7, v169
	v_readlane_b32 s8, v250, 58
	v_lshl_add_u64 v[2:3], v[2:3], 0, v[6:7]
	v_lshlrev_b64 v[0:1], 7, v[0:1]
	v_readlane_b32 s9, v250, 59
	global_load_dwordx4 v[132:135], v[2:3], off offset:2048
	global_load_dwordx4 v[116:119], v[2:3], off offset:2112
	v_lshl_add_u64 v[2:3], s[8:9], 0, v[0:1]
	v_readlane_b32 s8, v250, 60
	v_readlane_b32 s9, v250, 61
	v_lshlrev_b32_e32 v6, 5, v5
	v_lshl_add_u64 v[2:3], v[2:3], 0, v[6:7]
	v_lshl_add_u64 v[0:1], s[8:9], 0, v[0:1]
	v_lshl_add_u64 v[0:1], v[0:1], 0, v[6:7]
	global_load_dwordx4 v[96:99], v[2:3], off offset:16
	global_load_dwordx4 v[104:107], v[2:3], off
	global_load_dwordx4 v[100:103], v[0:1], off offset:16
	global_load_dwordx4 v[108:111], v[0:1], off
	s_lshl_b32 s24, s12, 6
	v_lshlrev_b32_e32 v136, 3, v5
	v_mov_b32_e32 v137, v169
	s_mov_b64 s[8:9], 0
	v_mov_b64_e32 v[0:1], s[10:11]
	v_mov_b64_e32 v[2:3], s[24:25]
	v_mov_b64_e32 v[40:41], v[136:137]

.LBB0_290:
	s_andn2_b64 vcc, exec, s[2:3]
	s_cbranch_vccnz .LBB0_467
	v_readlane_b32 s2, v250, 4
	v_readlane_b32 s3, v250, 5
	s_mov_b64 s[0:1], -1
	s_and_b64 vcc, exec, s[2:3]
	s_cbranch_vccz .LBB0_306
	v_readlane_b32 s0, v248, 27
	v_readlane_b32 s1, v248, 28
	v_mov_b32_e32 v24, v216
	s_andn2_b64 vcc, exec, s[0:1]
	s_cbranch_vccnz .LBB0_305
	v_readlane_b32 s0, v248, 34
	s_waitcnt vmcnt(0)
	v_add_u32_e32 v20, 0x200, v24
	v_and_b32_e32 v32, 63, v24
	v_lshlrev_b32_e32 v0, 4, v24
	v_readlane_b32 s1, v248, 35
	v_readlane_b32 s4, v248, 31
	v_ashrrev_i32_e32 v34, 4, v24
	v_ashrrev_i32_e32 v38, 4, v20
	v_and_b32_e32 v168, 0xf0, v0
	v_readlane_b32 s5, v248, 32
	v_or_b32_e32 v2, s4, v32
	s_waitcnt lgkmcnt(0)
	v_mov_b64_e32 v[0:1], s[0:1]
	s_movk_i32 s3, 0x1800
	v_ashrrev_i32_e32 v35, 31, v34
	v_ashrrev_i32_e32 v39, 31, v38
	v_lshl_add_u64 v[8:9], s[0:1], 0, v[168:169]
	v_mad_u64_u32 v[16:17], s[0:1], v2, s3, v[0:1]
	v_lshl_add_u64 v[0:1], s[4:5], 0, v[34:35]
	v_lshl_add_u64 v[10:11], s[4:5], 0, v[38:39]
	v_mad_u64_u32 v[4:5], s[0:1], v0, s3, v[8:9]
	v_ashrrev_i32_e32 v31, 3, v24
	v_mad_u64_u32 v[12:13], s[0:1], v10, s3, v[8:9]
	v_ashrrev_i32_e32 v48, 3, v20
	s_mul_i32 s2, s5, 0x1800
	v_mov_b32_e32 v0, v5
	v_and_b32_e32 v36, -8, v31
	v_mov_b32_e32 v8, v13
	v_and_b32_e32 v40, -8, v48
	v_add_u32_e32 v17, s2, v17
	v_mad_u64_u32 v[0:1], s[0:1], v1, s3, v[0:1]
	v_ashrrev_i32_e32 v37, 31, v36
	v_mad_u64_u32 v[8:9], s[0:1], v11, s3, v[8:9]
	v_ashrrev_i32_e32 v41, 31, v40
	v_mov_b32_e32 v5, v0
	v_lshl_add_u64 v[18:19], v[36:37], 1, v[16:17]
	v_mov_b32_e32 v13, v8
	v_lshl_add_u64 v[20:21], v[40:41], 1, v[16:17]
	global_load_dwordx4 v[0:3], v[4:5], off
	s_nop 0
	global_load_dwordx4 v[4:7], v[4:5], off offset:1024
	s_nop 0
	global_load_dwordx4 v[8:11], v[12:13], off
	s_nop 0
	global_load_dwordx4 v[12:15], v[12:13], off offset:1024
	s_nop 0
	global_load_dwordx4 v[16:19], v[18:19], off offset:2048
	s_nop 0
	global_load_dwordx4 v[20:23], v[20:21], off offset:2048
	v_ashrrev_i32_e32 v26, 6, v24
	v_ashrrev_i32_e32 v28, 7, v24
	v_readlane_b32 s2, v248, 40
	v_lshl_add_u32 v52, v32, 2, 0
	v_mul_u32_u24_e32 v27, 0x11c, v32
	v_lshlrev_b32_e32 v29, 4, v26
	v_and_b32_e32 v25, 15, v24
	v_readlane_b32 s3, v248, 41
	v_add3_u32 v116, v52, v27, v29
	v_lshlrev_b32_e32 v27, 4, v28
	v_lshrrev_b32_e32 v44, 2, v24
	v_and_b32_e32 v57, 48, v24
	v_lshl_add_u64 v[42:43], s[2:3], 0, v[168:169]
	v_lshlrev_b32_e32 v30, 3, v32
	v_readlane_b32 s2, v246, 24
	v_cmp_gt_u32_e64 s[40:41], 64, v24
	v_and_or_b32 v55, v44, 12, v27
	v_or_b32_e32 v56, v27, v25
	v_add_u32_e32 v24, 0, v57
	v_or_b32_e32 v27, v29, v25
	s_movk_i32 s4, 0x90
	v_add_u32_e32 v114, s2, v30
	s_movk_i32 s6, 0x110
	v_mad_u64_u32 v[46:47], s[2:3], v27, s4, v[24:25]
	v_ashrrev_i32_e32 v27, 31, v26
	v_mad_u64_u32 v[44:45], s[2:3], v56, s6, v[24:25]
	v_lshlrev_b64 v[50:51], 12, v[26:27]
	v_mul_lo_u32 v27, v56, s4
	v_readlane_b32 s16, v246, 25
	v_lshlrev_b32_e32 v33, 1, v32
	v_add_u32_e32 v49, 0, v168
	v_readlane_b32 s5, v246, 23
	v_add3_u32 v45, s16, v27, v57
	v_mul_lo_u32 v27, v34, s6
	v_add_u32_e32 v60, s5, v33
	v_add_u32_e32 v47, v49, v27
	v_mul_lo_u32 v27, v36, s4
	v_add_u32_e32 v117, v60, v27
	v_add3_u32 v118, s5, v27, v33
	v_or_b32_e32 v27, 7, v31
	v_lshl_or_b32 v31, v26, 3, 1
	v_and_b32_e32 v54, 1, v26
	v_mul_lo_u32 v62, v27, s4
	v_mul_lo_u32 v27, v38, s6
	v_mul_lo_u32 v31, v31, s6
	v_readlane_b32 s0, v246, 38
	v_lshlrev_b32_e32 v53, 1, v54
	v_add_u32_e32 v119, v49, v27
	v_mul_lo_u32 v27, v40, s4
	v_add_u32_e32 v123, v52, v31
	v_lshl_or_b32 v31, v54, 5, v25
	s_cmp_eq_u32 s0, 1
	v_add_u32_e32 v120, v60, v27
	v_add3_u32 v121, s5, v27, v33
	v_or_b32_e32 v27, 7, v48
	s_movk_i32 s2, 0x880
	v_cmp_gt_i32_e32 vcc, v53, v28
	v_or_b32_e32 v48, 1, v55
	v_cmp_gt_i32_e64 s[8:9], v31, v55
	s_cselect_b64 s[0:1], -1, 0
	v_mul_lo_u32 v63, v27, s4
	v_mul_lo_u32 v27, v26, s2
	v_or_b32_e32 v49, 2, v55
	s_or_b64 s[2:3], vcc, s[8:9]
	v_cmp_gt_i32_e64 s[8:9], v31, v48
	v_add_u32_e32 v122, v52, v27
	v_or_b32_e32 v52, 3, v55
	s_or_b64 s[10:11], vcc, s[8:9]
	v_cmp_gt_i32_e64 s[8:9], v31, v49
	v_add_u32_e32 v61, s5, v57
	v_cmp_le_i32_e64 s[58:59], v53, v28
	v_cmp_lt_i32_e64 s[60:61], v53, v28
	v_cmp_ge_i32_e64 s[6:7], v53, v28
	v_or_b32_e32 v53, 16, v31
	s_or_b64 s[12:13], vcc, s[8:9]
	v_cmp_gt_i32_e64 s[8:9], v31, v52
	v_mul_u32_u24_e32 v64, 0x110, v31
	v_mul_lo_u32 v65, v55, s4
	v_mad_u32_u24 v130, v25, s4, v61
	v_lshl_add_u32 v70, v31, 1, s16
	s_or_b64 s[8:9], vcc, s[8:9]
	v_cmp_gt_i32_e32 vcc, v53, v55
	v_lshlrev_b32_e32 v31, 1, v53
	v_readlane_b32 s4, v247, 26
	s_or_b64 s[14:15], s[6:7], vcc
	v_add3_u32 v131, s16, v65, v31
	v_cmp_gt_i32_e32 vcc, v53, v48
	v_mov_b32_e32 v31, v169
	v_readlane_b32 s5, v247, 27
	s_or_b64 s[16:17], s[6:7], vcc
	v_cmp_gt_i32_e32 vcc, v53, v49
	v_lshl_add_u64 v[48:49], s[4:5], 0, v[30:31]
	v_readlane_b32 s4, v247, 30
	v_readlane_b32 s5, v247, 31
	v_ashrrev_i32_e32 v29, 31, v28
	s_or_b64 s[18:19], s[6:7], vcc
	v_lshl_add_u64 v[50:51], s[4:5], 0, v[50:51]
	v_readlane_b32 s4, v247, 34
	v_cmp_gt_i32_e32 vcc, v53, v52
	v_lshlrev_b64 v[52:53], 12, v[28:29]
	v_readlane_b32 s5, v247, 35
	v_lshlrev_b32_e32 v168, 2, v54
	v_lshl_or_b32 v56, v54, 6, v25
	v_lshl_add_u64 v[52:53], s[4:5], 0, v[52:53]
	v_readlane_b32 s4, v247, 42
	v_readlane_b32 s5, v247, 43
	v_or_b32_e32 v57, 16, v56
	v_lshl_add_u32 v115, v26, 9, v114
	v_lshl_add_u64 v[28:29], v[28:29], 3, s[4:5]
	v_lshl_add_u64 v[28:29], v[28:29], 0, v[168:169]
	v_lshlrev_b64 v[28:29], 9, v[28:29]
	v_readlane_b32 s4, v247, 44
	v_cmp_lt_i32_e64 s[42:43], 0, v26
	v_cmp_lt_i32_e64 s[44:45], 1, v26
	v_cmp_lt_i32_e64 s[46:47], 2, v26
	v_cmp_lt_i32_e64 s[48:49], 3, v26
	v_cmp_lt_i32_e64 s[50:51], 4, v26
	v_cmp_lt_i32_e64 s[52:53], 5, v26
	v_cmp_lt_i32_e64 s[54:55], 6, v26
	v_cmp_lt_i32_e64 s[56:57], 7, v26
	v_lshlrev_b32_e32 v26, 7, v34
	v_lshlrev_b32_e32 v58, 7, v38
	v_mul_u32_u24_e32 v66, 0x90, v56
	v_mul_u32_u24_e32 v67, 0x90, v57
	v_or_b32_e32 v57, 32, v56
	v_or_b32_e32 v56, 48, v56
	s_or_b64 s[22:23], s[6:7], vcc
	v_lshlrev_b32_e32 v54, 11, v54
	v_mov_b32_e32 v55, v169
	v_or_b32_e32 v28, v28, v30
	s_mov_b64 s[6:7], 0x6000000
	v_lshlrev_b32_e32 v168, 4, v25
	v_readlane_b32 s5, v247, 45
	v_ashrrev_i32_e32 v27, 31, v26
	v_ashrrev_i32_e32 v59, 31, v58
	v_mul_u32_u24_e32 v68, 0x90, v57
	v_mul_u32_u24_e32 v69, 0x90, v56
	v_lshl_add_u64 v[52:53], v[52:53], 0, v[54:55]
	v_lshl_add_u64 v[54:55], v[28:29], 0, s[6:7]
	v_lshl_add_u64 v[28:29], s[4:5], 0, v[168:169]
	v_readlane_b32 s6, v247, 40
	v_add_u32_e32 v124, 0x110, v123
	v_add_u32_e32 v125, 0x220, v123
	v_add_u32_e32 v126, 0x330, v123
	v_add_u32_e32 v127, 0x440, v123
	v_add_u32_e32 v128, 0x550, v123
	v_add_u32_e32 v129, 0x660, v123
	v_add_u32_e32 v132, 0x90, v131
	v_add_u32_e32 v133, 0x120, v131
	v_add_u32_e32 v134, 0x1b0, v131
	v_lshl_add_u64 v[50:51], v[50:51], 0, v[30:31]
	v_lshl_add_u64 v[52:53], v[52:53], 0, v[30:31]
	v_lshl_add_u64 v[56:57], v[26:27], 1, v[28:29]
	v_lshl_add_u64 v[58:59], v[58:59], 1, v[28:29]
	v_add_u32_e32 v135, v60, v62
	v_add_u32_e32 v136, v60, v63
	v_add_u32_e32 v137, v70, v65
	v_add_u32_e32 v138, v61, v66
	v_add_u32_e32 v139, v61, v67
	v_add_u32_e32 v140, v61, v68
	v_add_u32_e32 v141, v61, v69
	v_add_u32_e32 v142, v24, v64
	v_readlane_b32 s5, v247, 36
	v_readlane_b32 s30, v248, 33
	s_mov_b32 s31, s6
	v_readlane_b32 s7, v247, 41
	s_mov_b32 s98, 0
	s_branch .LBB0_295
.LBB0_294:
	s_or_b64 exec, exec, s[6:7]
	s_nop 5
	v_cvt_pk_bf16_f32 v24, v24, s0
	v_cndmask_b32_e64 v24, v24, 0, s[14:15]
	ds_write_b16 v131, v24
	v_cvt_pk_bf16_f32 v24, v25, s0
	v_cndmask_b32_e64 v24, v24, 0, s[16:17]
	ds_write_b16 v132, v24
	v_cvt_pk_bf16_f32 v24, v26, s0
	v_cndmask_b32_e64 v24, v24, 0, s[18:19]
	ds_write_b16 v133, v24
	v_cvt_pk_bf16_f32 v24, v27, s0
	v_cndmask_b32_e64 v24, v24, 0, s[22:23]
	ds_write_b16 v134, v24
	ds_read_b128 v[28:31], v46 offset:52224
	ds_read_b128 v[24:27], v46 offset:52288
	ds_read_b128 v[60:63], v130
	ds_read_b128 v[64:67], v130 offset:64
	s_waitcnt lgkmcnt(1)
	v_mfma_f32_16x16x32_bf16 v[60:63], v[28:31], v[60:63], 0
	v_readlane_b32 s6, v247, 28
	v_readlane_b32 s7, v247, 29
	v_readlane_b32 s4, v247, 25
	s_waitcnt lgkmcnt(0)
	v_mfma_f32_16x16x32_bf16 v[60:63], v[24:27], v[64:67], v[60:63]
	v_lshl_add_u64 v[48:49], v[48:49], 0, s[6:7]
	ds_read_b128 v[66:69], v130 offset:2368
	v_readlane_b32 s6, v247, 32
	v_readlane_b32 s7, v247, 33
	s_add_i32 s30, s30, s4
	s_nop 2
	v_cvt_pk_bf16_f32 v64, v60, v61
	v_cvt_pk_bf16_f32 v65, v62, v63
	v_lshl_add_u64 v[60:61], s[38:39], 0, v[50:51]
	global_store_dwordx2 v[60:61], v[64:65], off
	ds_read_b128 v[62:65], v130 offset:2304
	s_waitcnt lgkmcnt(0)
	v_mfma_f32_16x16x32_bf16 v[62:65], v[28:31], v[62:65], 0
	v_lshl_add_u64 v[50:51], v[50:51], 0, s[6:7]
	v_readlane_b32 s6, v247, 38
	v_readlane_b32 s7, v247, 39
	v_mfma_f32_16x16x32_bf16 v[62:65], v[24:27], v[66:69], v[62:65]
	ds_read_b128 v[66:69], v130 offset:4672
	v_readlane_b32 s4, v247, 37
	s_add_i32 s5, s5, s4
	s_andn2_b64 vcc, exec, s[26:27]
	s_nop 3
	v_cvt_pk_bf16_f32 v62, v62, v63
	v_cvt_pk_bf16_f32 v63, v64, v65
	global_store_dwordx2 v[60:61], v[62:63], off offset:512
	ds_read_b128 v[62:65], v130 offset:4608
	s_waitcnt lgkmcnt(0)
	v_mfma_f32_16x16x32_bf16 v[62:65], v[28:31], v[62:65], 0
	v_mfma_f32_16x16x32_bf16 v[62:65], v[24:27], v[66:69], v[62:65]
	ds_read_b128 v[66:69], v130 offset:6976
	s_nop 6
	v_cvt_pk_bf16_f32 v62, v62, v63
	v_cvt_pk_bf16_f32 v63, v64, v65
	global_store_dwordx2 v[60:61], v[62:63], off offset:1024
	ds_read_b128 v[62:65], v130 offset:6912
	s_waitcnt lgkmcnt(0)
	v_mfma_f32_16x16x32_bf16 v[62:65], v[28:31], v[62:65], 0
	v_mfma_f32_16x16x32_bf16 v[62:65], v[24:27], v[66:69], v[62:65]
	ds_read_b128 v[66:69], v130 offset:9280
	s_nop 6
	v_cvt_pk_bf16_f32 v62, v62, v63
	v_cvt_pk_bf16_f32 v63, v64, v65
	global_store_dwordx2 v[60:61], v[62:63], off offset:1536
	ds_read_b128 v[62:65], v130 offset:9216
	s_waitcnt lgkmcnt(0)
	v_mfma_f32_16x16x32_bf16 v[62:65], v[28:31], v[62:65], 0
	v_mfma_f32_16x16x32_bf16 v[62:65], v[24:27], v[66:69], v[62:65]
	ds_read_b128 v[66:69], v130 offset:11584
	s_nop 6
	v_cvt_pk_bf16_f32 v62, v62, v63
	v_cvt_pk_bf16_f32 v63, v64, v65
	global_store_dwordx2 v[60:61], v[62:63], off offset:2048
	ds_read_b128 v[62:65], v130 offset:11520
	s_waitcnt lgkmcnt(0)
	v_mfma_f32_16x16x32_bf16 v[62:65], v[28:31], v[62:65], 0
	v_mfma_f32_16x16x32_bf16 v[62:65], v[24:27], v[66:69], v[62:65]
	ds_read_b128 v[66:69], v130 offset:13888
	s_nop 6
	v_cvt_pk_bf16_f32 v62, v62, v63
	v_cvt_pk_bf16_f32 v63, v64, v65
	global_store_dwordx2 v[60:61], v[62:63], off offset:2560
	ds_read_b128 v[62:65], v130 offset:13824
	s_waitcnt lgkmcnt(0)
	v_mfma_f32_16x16x32_bf16 v[62:65], v[28:31], v[62:65], 0
	v_mfma_f32_16x16x32_bf16 v[62:65], v[24:27], v[66:69], v[62:65]
	v_lshl_add_u64 v[68:69], s[38:39], 0, v[52:53]
	v_lshl_add_u64 v[52:53], v[52:53], 0, s[6:7]
	s_nop 5
	v_cvt_pk_bf16_f32 v62, v62, v63
	v_cvt_pk_bf16_f32 v63, v64, v65
	global_store_dwordx2 v[60:61], v[62:63], off offset:3072
	ds_read_b128 v[62:65], v130 offset:16128
	s_waitcnt lgkmcnt(0)
	v_mfma_f32_16x16x32_bf16 v[28:31], v[28:31], v[62:65], 0
	ds_read_b128 v[62:65], v130 offset:16192
	s_waitcnt lgkmcnt(0)
	v_mfma_f32_16x16x32_bf16 v[24:27], v[24:27], v[62:65], v[28:31]
	s_nop 4
	v_lshl_add_u64 v[28:29], s[38:39], 0, v[56:57]
	v_lshl_add_u64 v[56:57], v[56:57], 0, s[6:7]
	s_nop 0
	v_cvt_pk_bf16_f32 v24, v24, v25
	v_cvt_pk_bf16_f32 v25, v26, v27
	global_store_dwordx2 v[60:61], v[24:25], off offset:3584
	ds_read_b128 v[24:27], v47 offset:34816
	s_waitcnt lgkmcnt(0)
	global_store_dwordx4 v[28:29], v[24:27], off
	ds_read_b128 v[24:27], v119 offset:34816
	v_lshl_add_u64 v[28:29], s[38:39], 0, v[58:59]
	v_lshl_add_u64 v[58:59], v[58:59], 0, s[6:7]
	s_waitcnt lgkmcnt(0)
	global_store_dwordx4 v[28:29], v[24:27], off
	s_waitcnt lgkmcnt(0)
	s_barrier
	ds_read_b128 v[24:27], v45
	ds_read_b128 v[28:31], v45 offset:64
	ds_read_b128 v[60:63], v138
	ds_read_b128 v[64:67], v138 offset:64
	s_waitcnt lgkmcnt(1)
	v_mfma_f32_16x16x32_bf16 v[60:63], v[24:27], v[60:63], 0
	s_waitcnt lgkmcnt(0)
	v_mfma_f32_16x16x32_bf16 v[60:63], v[28:31], v[64:67], v[60:63]
	ds_read_b128 v[64:67], v139 offset:64
	s_nop 6
	v_cvt_pk_bf16_f32 v60, v60, v61
	v_cvt_pk_bf16_f32 v61, v62, v63
	v_lshl_add_u64 v[62:63], s[38:39], 0, v[54:55]
	global_store_dwordx2 v[62:63], v[60:61], off
	ds_read_b128 v[60:63], v139
	s_waitcnt lgkmcnt(0)
	v_mfma_f32_16x16x32_bf16 v[60:63], v[24:27], v[60:63], 0
	v_lshl_add_u64 v[54:55], v[54:55], 0, s[6:7]
	v_mfma_f32_16x16x32_bf16 v[60:63], v[28:31], v[64:67], v[60:63]
	ds_read_b128 v[64:67], v140 offset:64
	s_nop 6
	v_cvt_pk_bf16_f32 v60, v60, v61
	v_cvt_pk_bf16_f32 v61, v62, v63
	global_store_dwordx2 v[68:69], v[60:61], off offset:-512
	ds_read_b128 v[60:63], v140
	s_waitcnt lgkmcnt(0)
	v_mfma_f32_16x16x32_bf16 v[60:63], v[24:27], v[60:63], 0
	v_mfma_f32_16x16x32_bf16 v[60:63], v[28:31], v[64:67], v[60:63]
	s_nop 7
	v_cvt_pk_bf16_f32 v60, v60, v61
	v_cvt_pk_bf16_f32 v61, v62, v63
	global_store_dwordx2 v[68:69], v[60:61], off
	ds_read_b128 v[60:63], v141
	s_waitcnt lgkmcnt(0)
	v_mfma_f32_16x16x32_bf16 v[24:27], v[24:27], v[60:63], 0
	ds_read_b128 v[60:63], v141 offset:64
	s_waitcnt lgkmcnt(0)
	v_mfma_f32_16x16x32_bf16 v[24:27], v[28:31], v[60:63], v[24:27]
	s_nop 7
	v_cvt_pk_bf16_f32 v24, v24, v25
	v_cvt_pk_bf16_f32 v25, v26, v27
	global_store_dwordx2 v[68:69], v[24:25], off offset:512
	s_waitcnt lgkmcnt(0)
	s_barrier
	s_cbranch_vccz .LBB0_305
	s_mov_b32 s98, 1

.LBB0_297:
	v_readlane_b32 s6, v246, 7
	s_add_i32 s31, s31, s6
	s_cmpk_gt_i32 s31, 0x7ff
	s_cselect_b64 s[26:27], -1, 0
	s_and_b64 vcc, exec, s[26:27]
	s_cmp_lg_u32 s98, 0
	s_cbranch_scc0 .Liw_a_297_5
	s_waitcnt vmcnt(14)
	s_branch .Liw_b_297_5
.Liw_a_297_5:
	s_waitcnt vmcnt(5)
.Liw_b_297_5:
	ds_write_b128 v47, v[0:3]
	s_cbranch_scc1 .Liw_b_297_4
	s_waitcnt vmcnt(4)
.Liw_b_297_4:
	ds_write_b128 v47, v[4:7] offset:17408
	s_cbranch_scc1 .Liw_b_297_1
	s_waitcnt vmcnt(1)
.Liw_b_297_1:
	ds_write_b16 v117, v16
	ds_write_b16_d16_hi v118, v16 offset:144
	ds_write_b16 v118, v17 offset:288
	ds_write_b16_d16_hi v118, v17 offset:432
	ds_write_b16 v118, v18 offset:576
	ds_write_b16_d16_hi v118, v18 offset:720
	ds_write_b16 v118, v19 offset:864
	ds_write_b16_d16_hi v135, v19
	ds_write_b128 v119, v[8:11]
	ds_write_b128 v119, v[12:15] offset:17408
	s_cbranch_scc1 .Liw_b_297_0
	s_waitcnt vmcnt(0)
.Liw_b_297_0:
	ds_write_b16 v120, v20
	ds_write_b16_d16_hi v121, v20 offset:144
	ds_write_b16 v121, v21 offset:288
	ds_write_b16_d16_hi v121, v21 offset:432
	ds_write_b16 v121, v22 offset:576
	ds_write_b16_d16_hi v121, v22 offset:720
	ds_write_b16 v121, v23 offset:864
	ds_write_b16_d16_hi v136, v23
	v_readlane_b32 s7, v246, 8
	s_cbranch_vccnz .LBB0_299
	s_ashr_i32 s6, s31, 8
	s_ashr_i32 s7, s6, 31
	s_lshl_b64 s[6:7], s[6:7], 12
	s_and_b32 s24, s5, 0xfc0
	v_readlane_b32 s34, v246, 36
	s_or_b32 s6, s6, s24
	v_readlane_b32 s4, v247, 25
	v_readlane_b32 s35, v246, 37
	s_add_i32 s24, s4, s30
	v_or_b32_e32 v2, s6, v32
	v_mov_b64_e32 v[0:1], s[34:35]
	s_movk_i32 s4, 0x1800
	s_and_b32 s24, s24, 0x180
	v_mad_u64_u32 v[0:1], s[36:37], v2, s4, v[0:1]
	s_lshl_b32 s24, s24, 1
	v_mad_i32_i24 v1, s7, v224, v1
	v_lshl_add_u64 v[8:9], v[42:43], 0, s[24:25]
	v_lshl_add_u64 v[16:17], v[0:1], 0, s[24:25]
	v_lshl_add_u64 v[0:1], s[6:7], 0, v[34:35]
	v_lshl_add_u64 v[10:11], s[6:7], 0, v[38:39]
	v_mad_u64_u32 v[4:5], s[36:37], v0, s4, v[8:9]
	v_mad_u64_u32 v[12:13], s[6:7], v10, s4, v[8:9]
	v_mad_i32_i24 v5, v1, s4, v5
	v_lshl_add_u64 v[18:19], v[36:37], 1, v[16:17]
	v_mad_i32_i24 v13, v11, s4, v13
	v_lshl_add_u64 v[20:21], v[40:41], 1, v[16:17]
	global_load_dwordx4 v[0:3], v[4:5], off
	s_nop 0
	global_load_dwordx4 v[4:7], v[4:5], off offset:1024
	s_nop 0
	global_load_dwordx4 v[8:11], v[12:13], off
	s_nop 0
	global_load_dwordx4 v[12:15], v[12:13], off offset:1024
	s_nop 0
	global_load_dwordx4 v[16:19], v[18:19], off offset:2048
	s_nop 0
	global_load_dwordx4 v[20:23], v[20:21], off offset:2048

.LBB0_306:
	s_and_b64 vcc, exec, s[0:1]
	s_cbranch_vccz .LBB0_321
	v_readlane_b32 s0, v248, 36
	v_readlane_b32 s1, v248, 37
	v_mov_b32_e32 v24, v216
	s_andn2_b64 vcc, exec, s[0:1]
	s_cbranch_vccnz .LBB0_320
	v_readlane_b32 s0, v248, 42
	s_waitcnt vmcnt(0)
	v_add_u32_e32 v20, 0x200, v24
	v_and_b32_e32 v32, 63, v24
	v_lshlrev_b32_e32 v0, 4, v24
	v_readlane_b32 s1, v248, 43
	v_readlane_b32 s4, v248, 38
	v_ashrrev_i32_e32 v34, 4, v24
	v_ashrrev_i32_e32 v38, 4, v20
	v_and_b32_e32 v168, 0xf0, v0
	v_readlane_b32 s5, v248, 39
	v_or_b32_e32 v2, s4, v32
	s_waitcnt lgkmcnt(0)
	v_mov_b64_e32 v[0:1], s[0:1]
	s_movk_i32 s3, 0x1800
	v_ashrrev_i32_e32 v35, 31, v34
	v_ashrrev_i32_e32 v39, 31, v38
	v_lshl_add_u64 v[8:9], s[0:1], 0, v[168:169]
	v_mad_u64_u32 v[16:17], s[0:1], v2, s3, v[0:1]
	v_lshl_add_u64 v[0:1], s[4:5], 0, v[34:35]
	v_lshl_add_u64 v[10:11], s[4:5], 0, v[38:39]
	v_mad_u64_u32 v[4:5], s[0:1], v0, s3, v[8:9]
	v_ashrrev_i32_e32 v31, 3, v24
	v_mad_u64_u32 v[12:13], s[0:1], v10, s3, v[8:9]
	v_ashrrev_i32_e32 v48, 3, v20
	s_mul_i32 s2, s5, 0x1800
	v_mov_b32_e32 v0, v5
	v_and_b32_e32 v36, -8, v31
	v_mov_b32_e32 v8, v13
	v_and_b32_e32 v40, -8, v48
	v_add_u32_e32 v17, s2, v17
	v_mad_u64_u32 v[0:1], s[0:1], v1, s3, v[0:1]
	v_ashrrev_i32_e32 v37, 31, v36
	v_mad_u64_u32 v[8:9], s[0:1], v11, s3, v[8:9]
	v_ashrrev_i32_e32 v41, 31, v40
	v_mov_b32_e32 v5, v0
	v_lshl_add_u64 v[18:19], v[36:37], 1, v[16:17]
	v_mov_b32_e32 v13, v8
	v_lshl_add_u64 v[20:21], v[40:41], 1, v[16:17]
	global_load_dwordx4 v[0:3], v[4:5], off
	s_nop 0
	global_load_dwordx4 v[4:7], v[4:5], off offset:1024
	s_nop 0
	global_load_dwordx4 v[8:11], v[12:13], off
	s_nop 0
	global_load_dwordx4 v[12:15], v[12:13], off offset:1024
	s_nop 0
	global_load_dwordx4 v[16:19], v[18:19], off offset:2048
	s_nop 0
	global_load_dwordx4 v[20:23], v[20:21], off offset:2048
	v_ashrrev_i32_e32 v26, 6, v24
	v_ashrrev_i32_e32 v28, 7, v24
	v_readlane_b32 s2, v248, 40
	v_lshl_add_u32 v52, v32, 2, 0
	v_mul_u32_u24_e32 v27, 0x11c, v32
	v_lshlrev_b32_e32 v29, 4, v26
	v_and_b32_e32 v25, 15, v24
	v_readlane_b32 s3, v248, 41
	v_add3_u32 v116, v52, v27, v29
	v_lshlrev_b32_e32 v27, 4, v28
	v_lshrrev_b32_e32 v44, 2, v24
	v_and_b32_e32 v57, 48, v24
	v_lshl_add_u64 v[42:43], s[2:3], 0, v[168:169]
	v_lshlrev_b32_e32 v30, 3, v32
	v_readlane_b32 s2, v246, 24
	v_cmp_gt_u32_e64 s[40:41], 64, v24
	v_and_or_b32 v55, v44, 12, v27
	v_or_b32_e32 v56, v27, v25
	v_add_u32_e32 v24, 0, v57
	v_or_b32_e32 v27, v29, v25
	s_movk_i32 s4, 0x90
	v_add_u32_e32 v114, s2, v30
	s_movk_i32 s6, 0x110
	v_mad_u64_u32 v[46:47], s[2:3], v27, s4, v[24:25]
	v_ashrrev_i32_e32 v27, 31, v26
	v_mad_u64_u32 v[44:45], s[2:3], v56, s6, v[24:25]
	v_lshlrev_b64 v[50:51], 12, v[26:27]
	v_mul_lo_u32 v27, v56, s4
	v_readlane_b32 s16, v246, 25
	v_lshlrev_b32_e32 v33, 1, v32
	v_add_u32_e32 v49, 0, v168
	v_readlane_b32 s5, v246, 23
	v_add3_u32 v45, s16, v27, v57
	v_mul_lo_u32 v27, v34, s6
	v_add_u32_e32 v60, s5, v33
	v_add_u32_e32 v47, v49, v27
	v_mul_lo_u32 v27, v36, s4
	v_add_u32_e32 v117, v60, v27
	v_add3_u32 v118, s5, v27, v33
	v_or_b32_e32 v27, 7, v31
	v_lshl_or_b32 v31, v26, 3, 1
	v_and_b32_e32 v54, 1, v26
	v_mul_lo_u32 v62, v27, s4
	v_mul_lo_u32 v27, v38, s6
	v_mul_lo_u32 v31, v31, s6
	v_readlane_b32 s0, v246, 38
	v_lshlrev_b32_e32 v53, 1, v54
	v_add_u32_e32 v119, v49, v27
	v_mul_lo_u32 v27, v40, s4
	v_add_u32_e32 v123, v52, v31
	v_lshl_or_b32 v31, v54, 5, v25
	s_cmp_eq_u32 s0, 1
	v_add_u32_e32 v120, v60, v27
	v_add3_u32 v121, s5, v27, v33
	v_or_b32_e32 v27, 7, v48
	s_movk_i32 s2, 0x880
	v_cmp_gt_i32_e32 vcc, v53, v28
	v_or_b32_e32 v48, 1, v55
	v_cmp_gt_i32_e64 s[8:9], v31, v55
	s_cselect_b64 s[0:1], -1, 0
	v_mul_lo_u32 v63, v27, s4
	v_mul_lo_u32 v27, v26, s2
	v_or_b32_e32 v49, 2, v55
	s_or_b64 s[2:3], vcc, s[8:9]
	v_cmp_gt_i32_e64 s[8:9], v31, v48
	v_add_u32_e32 v122, v52, v27
	v_or_b32_e32 v52, 3, v55
	s_or_b64 s[10:11], vcc, s[8:9]
	v_cmp_gt_i32_e64 s[8:9], v31, v49
	v_add_u32_e32 v61, s5, v57
	v_cmp_le_i32_e64 s[58:59], v53, v28
	v_cmp_lt_i32_e64 s[60:61], v53, v28
	v_cmp_ge_i32_e64 s[6:7], v53, v28
	v_or_b32_e32 v53, 16, v31
	s_or_b64 s[12:13], vcc, s[8:9]
	v_cmp_gt_i32_e64 s[8:9], v31, v52
	v_mul_u32_u24_e32 v64, 0x110, v31
	v_mul_lo_u32 v65, v55, s4
	v_mad_u32_u24 v130, v25, s4, v61
	v_lshl_add_u32 v70, v31, 1, s16
	s_or_b64 s[8:9], vcc, s[8:9]
	v_cmp_gt_i32_e32 vcc, v53, v55
	v_lshlrev_b32_e32 v31, 1, v53
	v_readlane_b32 s4, v247, 47
	s_or_b64 s[14:15], s[6:7], vcc
	v_add3_u32 v131, s16, v65, v31
	v_cmp_gt_i32_e32 vcc, v53, v48
	v_mov_b32_e32 v31, v169
	v_readlane_b32 s5, v247, 48
	s_or_b64 s[16:17], s[6:7], vcc
	v_cmp_gt_i32_e32 vcc, v53, v49
	v_lshl_add_u64 v[48:49], s[4:5], 0, v[30:31]
	v_readlane_b32 s4, v247, 49
	v_readlane_b32 s5, v247, 50
	v_ashrrev_i32_e32 v29, 31, v28
	s_or_b64 s[18:19], s[6:7], vcc
	v_lshl_add_u64 v[50:51], s[4:5], 0, v[50:51]
	v_readlane_b32 s4, v247, 51
	v_cmp_gt_i32_e32 vcc, v53, v52
	v_lshlrev_b64 v[52:53], 12, v[28:29]
	v_readlane_b32 s5, v247, 52
	v_lshlrev_b32_e32 v168, 2, v54
	v_lshl_or_b32 v56, v54, 6, v25
	v_lshl_add_u64 v[52:53], s[4:5], 0, v[52:53]
	v_readlane_b32 s4, v247, 59
	v_readlane_b32 s5, v247, 60
	v_or_b32_e32 v57, 16, v56
	v_lshl_add_u32 v115, v26, 9, v114
	v_lshl_add_u64 v[28:29], v[28:29], 3, s[4:5]
	v_lshl_add_u64 v[28:29], v[28:29], 0, v[168:169]
	v_readlane_b32 s4, v247, 54
	v_lshlrev_b64 v[28:29], 9, v[28:29]
	v_readlane_b32 s5, v247, 55
	v_cmp_lt_i32_e64 s[42:43], 0, v26
	v_cmp_lt_i32_e64 s[44:45], 1, v26
	v_lshl_add_u64 v[28:29], s[4:5], 0, v[28:29]
	v_readlane_b32 s4, v247, 61
	v_cmp_lt_i32_e64 s[46:47], 2, v26
	v_cmp_lt_i32_e64 s[48:49], 3, v26
	v_cmp_lt_i32_e64 s[50:51], 4, v26
	v_cmp_lt_i32_e64 s[52:53], 5, v26
	v_cmp_lt_i32_e64 s[54:55], 6, v26
	v_cmp_lt_i32_e64 s[56:57], 7, v26
	v_lshlrev_b32_e32 v26, 7, v34
	v_lshlrev_b32_e32 v58, 7, v38
	v_mul_u32_u24_e32 v66, 0x90, v56
	v_mul_u32_u24_e32 v67, 0x90, v57
	v_or_b32_e32 v57, 32, v56
	v_or_b32_e32 v56, 48, v56
	v_lshlrev_b32_e32 v54, 11, v54
	v_mov_b32_e32 v55, v169
	v_lshlrev_b32_e32 v168, 4, v25
	v_readlane_b32 s5, v247, 62
	v_ashrrev_i32_e32 v27, 31, v26
	v_ashrrev_i32_e32 v59, 31, v58
	v_mul_u32_u24_e32 v68, 0x90, v57
	v_mul_u32_u24_e32 v69, 0x90, v56
	v_lshl_add_u64 v[52:53], v[52:53], 0, v[54:55]
	v_lshl_add_u64 v[54:55], v[28:29], 0, v[30:31]
	v_lshl_add_u64 v[28:29], s[4:5], 0, v[168:169]
	v_add_u32_e32 v124, 0x110, v123
	v_add_u32_e32 v125, 0x220, v123
	v_add_u32_e32 v126, 0x330, v123
	v_add_u32_e32 v127, 0x440, v123
	v_add_u32_e32 v128, 0x550, v123
	v_add_u32_e32 v129, 0x660, v123
	v_add_u32_e32 v132, 0x90, v131
	v_add_u32_e32 v133, 0x120, v131
	s_or_b64 s[22:23], s[6:7], vcc
	v_add_u32_e32 v134, 0x1b0, v131
	v_lshl_add_u64 v[50:51], v[50:51], 0, v[30:31]
	v_lshl_add_u64 v[52:53], v[52:53], 0, v[30:31]
	v_lshl_add_u64 v[56:57], v[26:27], 1, v[28:29]
	v_lshl_add_u64 v[58:59], v[58:59], 1, v[28:29]
	v_add_u32_e32 v135, v60, v62
	v_add_u32_e32 v136, v60, v63
	v_add_u32_e32 v137, v70, v65
	v_add_u32_e32 v138, v61, v66
	v_add_u32_e32 v139, v61, v67
	v_add_u32_e32 v140, v61, v68
	v_add_u32_e32 v141, v61, v69
	v_add_u32_e32 v142, v24, v64
	v_readlane_b32 s5, v247, 53
	v_readlane_b32 s30, v247, 46
	v_readlane_b32 s6, v247, 57
	v_readlane_b32 s7, v247, 58
	s_mov_b32 s98, 0
	s_branch .LBB0_310
.LBB0_309:
	s_or_b64 exec, exec, s[6:7]
	s_nop 5
	v_cvt_pk_bf16_f32 v24, v24, s0
	v_cndmask_b32_e64 v24, v24, 0, s[14:15]
	ds_write_b16 v131, v24
	v_cvt_pk_bf16_f32 v24, v25, s0
	v_cndmask_b32_e64 v24, v24, 0, s[16:17]
	ds_write_b16 v132, v24
	v_cvt_pk_bf16_f32 v24, v26, s0
	v_cndmask_b32_e64 v24, v24, 0, s[18:19]
	ds_write_b16 v133, v24
	v_cvt_pk_bf16_f32 v24, v27, s0
	v_cndmask_b32_e64 v24, v24, 0, s[22:23]
	ds_write_b16 v134, v24
	ds_read_b128 v[28:31], v46 offset:52224
	ds_read_b128 v[24:27], v46 offset:52288
	ds_read_b128 v[60:63], v130
	ds_read_b128 v[64:67], v130 offset:64
	s_waitcnt lgkmcnt(1)
	v_mfma_f32_16x16x32_bf16 v[60:63], v[28:31], v[60:63], 0
	s_mov_b64 s[6:7], 0x4000
	v_lshl_add_u64 v[48:49], v[48:49], 0, s[6:7]
	s_mov_b64 s[6:7], 0x100000
	s_waitcnt lgkmcnt(0)
	v_mfma_f32_16x16x32_bf16 v[60:63], v[24:27], v[64:67], v[60:63]
	s_add_i32 s30, s30, 64
	ds_read_b128 v[66:69], v130 offset:2368
	s_addk_i32 s5, 0x800
	s_andn2_b64 vcc, exec, s[26:27]
	s_nop 3
	v_cvt_pk_bf16_f32 v64, v60, v61
	v_cvt_pk_bf16_f32 v65, v62, v63
	v_lshl_add_u64 v[60:61], s[38:39], 0, v[50:51]
	global_store_dwordx2 v[60:61], v[64:65], off
	ds_read_b128 v[62:65], v130 offset:2304
	s_waitcnt lgkmcnt(0)
	v_mfma_f32_16x16x32_bf16 v[62:65], v[28:31], v[62:65], 0
	v_lshl_add_u64 v[50:51], v[50:51], 0, s[6:7]
	s_mov_b32 s6, s31
	v_mfma_f32_16x16x32_bf16 v[62:65], v[24:27], v[66:69], v[62:65]
	ds_read_b128 v[66:69], v130 offset:4672
	s_nop 6
	v_cvt_pk_bf16_f32 v62, v62, v63
	v_cvt_pk_bf16_f32 v63, v64, v65
	global_store_dwordx2 v[60:61], v[62:63], off offset:512
	ds_read_b128 v[62:65], v130 offset:4608
	s_waitcnt lgkmcnt(0)
	v_mfma_f32_16x16x32_bf16 v[62:65], v[28:31], v[62:65], 0
	v_mfma_f32_16x16x32_bf16 v[62:65], v[24:27], v[66:69], v[62:65]
	ds_read_b128 v[66:69], v130 offset:6976
	s_nop 6
	v_cvt_pk_bf16_f32 v62, v62, v63
	v_cvt_pk_bf16_f32 v63, v64, v65
	global_store_dwordx2 v[60:61], v[62:63], off offset:1024
	ds_read_b128 v[62:65], v130 offset:6912
	s_waitcnt lgkmcnt(0)
	v_mfma_f32_16x16x32_bf16 v[62:65], v[28:31], v[62:65], 0
	v_mfma_f32_16x16x32_bf16 v[62:65], v[24:27], v[66:69], v[62:65]
	ds_read_b128 v[66:69], v130 offset:9280
	s_nop 6
	v_cvt_pk_bf16_f32 v62, v62, v63
	v_cvt_pk_bf16_f32 v63, v64, v65
	global_store_dwordx2 v[60:61], v[62:63], off offset:1536
	ds_read_b128 v[62:65], v130 offset:9216
	s_waitcnt lgkmcnt(0)
	v_mfma_f32_16x16x32_bf16 v[62:65], v[28:31], v[62:65], 0
	v_mfma_f32_16x16x32_bf16 v[62:65], v[24:27], v[66:69], v[62:65]
	ds_read_b128 v[66:69], v130 offset:11584
	s_nop 6
	v_cvt_pk_bf16_f32 v62, v62, v63
	v_cvt_pk_bf16_f32 v63, v64, v65
	global_store_dwordx2 v[60:61], v[62:63], off offset:2048
	ds_read_b128 v[62:65], v130 offset:11520
	s_waitcnt lgkmcnt(0)
	v_mfma_f32_16x16x32_bf16 v[62:65], v[28:31], v[62:65], 0
	v_mfma_f32_16x16x32_bf16 v[62:65], v[24:27], v[66:69], v[62:65]
	ds_read_b128 v[66:69], v130 offset:13888
	s_nop 6
	v_cvt_pk_bf16_f32 v62, v62, v63
	v_cvt_pk_bf16_f32 v63, v64, v65
	global_store_dwordx2 v[60:61], v[62:63], off offset:2560
	ds_read_b128 v[62:65], v130 offset:13824
	s_waitcnt lgkmcnt(0)
	v_mfma_f32_16x16x32_bf16 v[62:65], v[28:31], v[62:65], 0
	v_mfma_f32_16x16x32_bf16 v[62:65], v[24:27], v[66:69], v[62:65]
	v_lshl_add_u64 v[68:69], s[38:39], 0, v[52:53]
	v_lshl_add_u64 v[52:53], v[52:53], 0, s[28:29]
	s_nop 5
	v_cvt_pk_bf16_f32 v62, v62, v63
	v_cvt_pk_bf16_f32 v63, v64, v65
	global_store_dwordx2 v[60:61], v[62:63], off offset:3072
	ds_read_b128 v[62:65], v130 offset:16128
	s_waitcnt lgkmcnt(0)
	v_mfma_f32_16x16x32_bf16 v[28:31], v[28:31], v[62:65], 0
	ds_read_b128 v[62:65], v130 offset:16192
	s_waitcnt lgkmcnt(0)
	v_mfma_f32_16x16x32_bf16 v[24:27], v[24:27], v[62:65], v[28:31]
	s_nop 4
	v_lshl_add_u64 v[28:29], s[38:39], 0, v[56:57]
	v_lshl_add_u64 v[56:57], v[56:57], 0, s[28:29]
	s_nop 0
	v_cvt_pk_bf16_f32 v24, v24, v25
	v_cvt_pk_bf16_f32 v25, v26, v27
	global_store_dwordx2 v[60:61], v[24:25], off offset:3584
	ds_read_b128 v[24:27], v47 offset:34816
	s_waitcnt lgkmcnt(0)
	global_store_dwordx4 v[28:29], v[24:27], off
	ds_read_b128 v[24:27], v119 offset:34816
	v_lshl_add_u64 v[28:29], s[38:39], 0, v[58:59]
	v_lshl_add_u64 v[58:59], v[58:59], 0, s[28:29]
	s_waitcnt lgkmcnt(0)
	global_store_dwordx4 v[28:29], v[24:27], off
	s_waitcnt lgkmcnt(0)
	s_barrier
	ds_read_b128 v[24:27], v45
	ds_read_b128 v[28:31], v45 offset:64
	ds_read_b128 v[60:63], v138
	ds_read_b128 v[64:67], v138 offset:64
	s_waitcnt lgkmcnt(1)
	v_mfma_f32_16x16x32_bf16 v[60:63], v[24:27], v[60:63], 0
	s_waitcnt lgkmcnt(0)
	v_mfma_f32_16x16x32_bf16 v[60:63], v[28:31], v[64:67], v[60:63]
	ds_read_b128 v[64:67], v139 offset:64
	s_nop 6
	v_cvt_pk_bf16_f32 v60, v60, v61
	v_cvt_pk_bf16_f32 v61, v62, v63
	v_lshl_add_u64 v[62:63], s[38:39], 0, v[54:55]
	global_store_dwordx2 v[62:63], v[60:61], off
	ds_read_b128 v[60:63], v139
	s_waitcnt lgkmcnt(0)
	v_mfma_f32_16x16x32_bf16 v[60:63], v[24:27], v[60:63], 0
	v_lshl_add_u64 v[54:55], v[54:55], 0, s[28:29]
	v_mfma_f32_16x16x32_bf16 v[60:63], v[28:31], v[64:67], v[60:63]
	ds_read_b128 v[64:67], v140 offset:64
	s_nop 6
	v_cvt_pk_bf16_f32 v60, v60, v61
	v_cvt_pk_bf16_f32 v61, v62, v63
	global_store_dwordx2 v[68:69], v[60:61], off offset:-512
	ds_read_b128 v[60:63], v140
	s_waitcnt lgkmcnt(0)
	v_mfma_f32_16x16x32_bf16 v[60:63], v[24:27], v[60:63], 0
	v_mfma_f32_16x16x32_bf16 v[60:63], v[28:31], v[64:67], v[60:63]
	s_nop 7
	v_cvt_pk_bf16_f32 v60, v60, v61
	v_cvt_pk_bf16_f32 v61, v62, v63
	global_store_dwordx2 v[68:69], v[60:61], off
	ds_read_b128 v[60:63], v141
	s_waitcnt lgkmcnt(0)
	v_mfma_f32_16x16x32_bf16 v[24:27], v[24:27], v[60:63], 0
	ds_read_b128 v[60:63], v141 offset:64
	s_waitcnt lgkmcnt(0)
	v_mfma_f32_16x16x32_bf16 v[24:27], v[28:31], v[60:63], v[24:27]
	s_nop 7
	v_cvt_pk_bf16_f32 v24, v24, v25
	v_cvt_pk_bf16_f32 v25, v26, v27
	global_store_dwordx2 v[68:69], v[24:25], off offset:512
	s_waitcnt lgkmcnt(0)
	s_barrier
	s_cbranch_vccz .LBB0_320
	s_mov_b32 s98, 1

.LBB0_312:
	s_add_i32 s31, s6, 32
	v_readlane_b32 s4, v248, 44
	s_cmp_ge_i32 s6, s4
	s_cselect_b64 s[26:27], -1, 0
	s_and_b64 vcc, exec, s[26:27]
	s_cmp_lg_u32 s98, 0
	s_cbranch_scc0 .Liw_a_312_5
	s_waitcnt vmcnt(14)
	s_branch .Liw_b_312_5

.Liw_b_312_0:
	ds_write_b16 v120, v20
	ds_write_b16_d16_hi v121, v20 offset:144
	ds_write_b16 v121, v21 offset:288
	ds_write_b16_d16_hi v121, v21 offset:432
	ds_write_b16 v121, v22 offset:576
	ds_write_b16_d16_hi v121, v22 offset:720
	ds_write_b16 v121, v23 offset:864
	ds_write_b16_d16_hi v136, v23
	s_cbranch_vccnz .LBB0_314
	s_ashr_i32 s6, s31, 8
	s_ashr_i32 s7, s6, 31
	s_lshl_b64 s[6:7], s[6:7], 12
	s_and_b32 s24, s5, 0xfc0
	v_readlane_b32 s34, v246, 36
	s_or_b32 s6, s6, s24
	v_readlane_b32 s35, v246, 37
	s_add_i32 s24, s30, 64
	v_or_b32_e32 v2, s6, v32
	v_mov_b64_e32 v[0:1], s[34:35]
	s_movk_i32 s4, 0x1800
	s_and_b32 s24, s24, 0x180
	v_mad_u64_u32 v[0:1], s[36:37], v2, s4, v[0:1]
	s_lshl_b32 s24, s24, 1
	v_mad_i32_i24 v1, s7, v224, v1
	v_lshl_add_u64 v[8:9], v[42:43], 0, s[24:25]
	v_lshl_add_u64 v[16:17], v[0:1], 0, s[24:25]
	v_lshl_add_u64 v[0:1], s[6:7], 0, v[34:35]
	v_lshl_add_u64 v[10:11], s[6:7], 0, v[38:39]
	v_mad_u64_u32 v[4:5], s[36:37], v0, s4, v[8:9]
	v_mad_u64_u32 v[12:13], s[6:7], v10, s4, v[8:9]
	v_mad_i32_i24 v5, v1, s4, v5
	v_lshl_add_u64 v[18:19], v[36:37], 1, v[16:17]
	v_mad_i32_i24 v13, v11, s4, v13
	v_lshl_add_u64 v[20:21], v[40:41], 1, v[16:17]
	global_load_dwordx4 v[0:3], v[4:5], off
	s_nop 0
	global_load_dwordx4 v[4:7], v[4:5], off offset:1024
	s_nop 0
	global_load_dwordx4 v[8:11], v[12:13], off
	s_nop 0
	global_load_dwordx4 v[12:15], v[12:13], off offset:1024
	s_nop 0
	global_load_dwordx4 v[16:19], v[18:19], off offset:2048
	s_nop 0
	global_load_dwordx4 v[20:23], v[20:21], off offset:2048
